# nt hint on the P0 rmsnorm row loads (x / memory rows are read once there)
# speedup vs baseline: 1.0341x; 1.0303x over previous
; #define GAS __attribute__((address_space(1)))
; __device__ __forceinline__ unsigned pk2(float lo, float hi) { const pkf2_t v = {lo, hi}; const pkb2_t b = __builtin_convertvector(v, pkb2_t); return __builtin_bit_cast(unsigned, b); }
; __device__ __forceinline__ void p0_rows(Frame& F) {
;     ...
;     for (int m = gw; m < MT + MEMR; m += 2 * NGW) {
;         const int m2 = m + NGW; const bool two = m2 < MT + MEMR;
;         const GAS f32x4* xa = (const GAS f32x4*)row_src(m) + F.lane; const GAS f32x4* xb = (const GAS f32x4*)row_src(two ? m2 : m) + F.lane;
;         f32x4 va[4], vb[4]; float sa = 0.f, sb = 0.f;
; #pragma unroll
;         for (int j = 0; j < 4; ++j) { va[j] = xa[64 * j]; vb[j] = xb[64 * j]; }
; #pragma unroll
;         for (int j = 0; j < 4; ++j) { sa += (va[j].x * va[j].x + va[j].y * va[j].y) + (va[j].z * va[j].z + va[j].w * va[j].w); sb += (vb[j].x * vb[j].x + vb[j].y * vb[j].y) + (vb[j].z * vb[j].z + vb[j].w * vb[j].w); }
;         const float ra = __builtin_amdgcn_rsqf(wave_sum(sa) * (1.f / D) + EPS), rb = __builtin_amdgcn_rsqf(wave_sum(sb) * (1.f / D) + EPS);
;         GAS unsigned long long* oa = (GAS unsigned long long*)row_dst(m) + F.lane; GAS unsigned long long* ob = (GAS unsigned long long*)row_dst(two ? m2 : m) + F.lane;
;         float* rstd1 = (float*)F.KK;
;         if (m < MT) { if (F.lane == 0) rstd1[m] = ra;
; #pragma unroll
;             for (int j = 0; j < 4; ++j) oa[64 * j] = (unsigned long long)pk2(va[j].x, va[j].y) | ((unsigned long long)pk2(va[j].z, va[j].w) << 32); }
;         else { const GAS f32x4* ga = (const GAS f32x4*)F.mem_norm_g + F.lane;
; #pragma unroll
;             for (int j = 0; j < 4; ++j) { const f32x4 g1 = ga[64 * j]; oa[64 * j] = (unsigned long long)pk2(va[j].x * ra * g1.x, va[j].y * ra * g1.y) | ((unsigned long long)pk2(va[j].z * ra * g1.z, va[j].w * ra * g1.w) << 32); } }
.LBB0_36:
	s_lshl_b64 s[10:11], s[22:23], 12
	s_add_u32 s4, s4, s10
	s_addc_u32 s5, s5, s11
	global_load_dwordx4 v[30:33], v51, s[4:5] nt
	global_load_dwordx4 v[26:29], v51, s[4:5] offset:1024 nt
	global_load_dwordx4 v[22:25], v51, s[4:5] offset:2048 nt
	global_load_dwordx4 v[18:21], v51, s[4:5] offset:3072 nt
	s_lshl_b64 s[4:5], s[8:9], 12
	s_add_u32 s2, s2, s4
	s_addc_u32 s3, s3, s5
	global_load_dwordx4 v[14:17], v51, s[2:3] nt
	global_load_dwordx4 v[10:13], v51, s[2:3] offset:1024 nt
	global_load_dwordx4 v[6:9], v51, s[2:3] offset:2048 nt
	global_load_dwordx4 v[2:5], v51, s[2:3] offset:3072 nt
	s_add_i32 s4, s16, 0xffffbc00
	s_ashr_i32 s17, s16, 31
	s_cmpk_lt_i32 s16, 0x4400
	s_cselect_b64 s[2:3], -1, 0
	s_and_b64 vcc, s[2:3], exec
	s_cselect_b32 s3, s17, 0
	s_cselect_b32 s2, s16, s4
	s_cselect_b32 s4, s65, s78
	s_cselect_b32 s5, s64, s89
	s_lshl_b64 s[2:3], s[2:3], 11
	s_add_u32 s2, s5, s2
	s_addc_u32 s3, s4, s3
	s_waitcnt vmcnt(7)
	v_mul_f32_e32 v38, v31, v31
	v_mul_f32_e32 v39, v33, v33
	s_waitcnt vmcnt(6)
	v_mul_f32_e32 v40, v27, v27
	v_mul_f32_e32 v42, v29, v29
	s_waitcnt vmcnt(5)
	v_mul_f32_e32 v43, v23, v23
	v_mul_f32_e32 v44, v25, v25
	v_fmac_f32_e32 v38, v30, v30
	v_fmac_f32_e32 v39, v32, v32
	v_fmac_f32_e32 v40, v26, v26
	v_fmac_f32_e32 v42, v28, v28
	s_waitcnt vmcnt(4)
	v_mul_f32_e32 v45, v19, v19
	v_mul_f32_e32 v53, v21, v21
	v_fmac_f32_e32 v43, v22, v22
	v_fmac_f32_e32 v44, v24, v24
	v_add_f32_e32 v38, v38, v39
	v_add_f32_e32 v40, v40, v42
	v_fmac_f32_e32 v45, v18, v18
	v_fmac_f32_e32 v53, v20, v20
	v_add_f32_e32 v43, v43, v44
	v_add_f32_e32 v38, v38, v40
	s_waitcnt vmcnt(2)
	v_mul_f32_e32 v42, v11, v11
	v_mul_f32_e32 v55, v13, v13
	s_waitcnt vmcnt(1)
	v_mul_f32_e32 v44, v7, v7
	v_mul_f32_e32 v56, v9, v9
	v_add_f32_e32 v45, v45, v53
	v_add_f32_e32 v38, v38, v43
	v_fmac_f32_e32 v42, v10, v10
	v_fmac_f32_e32 v55, v12, v12
	v_fmac_f32_e32 v44, v6, v6
	v_fmac_f32_e32 v56, v8, v8
	v_add_f32_e32 v38, v38, v45
	v_mul_f32_e32 v39, v15, v15
	s_waitcnt lgkmcnt(0)
	v_mul_f32_e32 v54, v17, v17
	v_add_f32_e32 v40, v42, v55
	v_add_f32_e32 v42, v44, v56
	ds_bpermute_b32 v44, v41, v38
	v_fmac_f32_e32 v39, v14, v14
	v_fmac_f32_e32 v54, v16, v16
	s_waitcnt vmcnt(0)
	v_mul_f32_e32 v53, v3, v3
	v_mul_f32_e32 v57, v5, v5
	v_add_f32_e32 v39, v39, v54
	v_fmac_f32_e32 v53, v2, v2
	v_fmac_f32_e32 v57, v4, v4
	v_add_f32_e32 v39, v39, v40
	v_add_f32_e32 v43, v53, v57
	v_add_f32_e32 v39, v39, v42
	v_add_f32_e32 v39, v39, v43
	s_waitcnt lgkmcnt(0)
	v_add_f32_e32 v38, v38, v44
	ds_bpermute_b32 v40, v41, v39
	ds_bpermute_b32 v42, v46, v38
	s_waitcnt lgkmcnt(1)
	v_add_f32_e32 v39, v39, v40
	s_waitcnt lgkmcnt(0)
	v_add_f32_e32 v38, v38, v42
	ds_bpermute_b32 v40, v46, v39
	ds_bpermute_b32 v42, v47, v38
	s_waitcnt lgkmcnt(1)
	v_add_f32_e32 v39, v39, v40
	s_waitcnt lgkmcnt(0)
	v_add_f32_e32 v38, v38, v42
	ds_bpermute_b32 v40, v47, v39
	ds_bpermute_b32 v42, v48, v38
	s_waitcnt lgkmcnt(1)
	v_add_f32_e32 v39, v39, v40
	s_waitcnt lgkmcnt(0)
	v_add_f32_e32 v38, v38, v42
	ds_bpermute_b32 v40, v48, v39
	ds_bpermute_b32 v42, v49, v38
	s_waitcnt lgkmcnt(1)
	v_add_f32_e32 v39, v39, v40
	s_waitcnt lgkmcnt(0)
	v_add_f32_e32 v38, v38, v42
	ds_bpermute_b32 v40, v49, v39
	ds_bpermute_b32 v42, v50, v38
	s_waitcnt lgkmcnt(1)
	v_add_f32_e32 v53, v39, v40
	s_waitcnt lgkmcnt(0)
	v_add_f32_e32 v38, v38, v42
	ds_bpermute_b32 v54, v50, v53
	v_fmamk_f32 v38, v38, 0x3a800000, v52
	v_rsq_f32_e32 v40, v38
	v_lshl_add_u64 v[38:39], s[2:3], 0, v[34:35]
	s_mov_b64 s[2:3], -1
	s_cbranch_vccnz .LBB0_38
	global_load_dwordx4 v[42:45], v[36:37], off nt
	v_pk_mul_f32 v[56:57], v[30:31], v[40:41] op_sel_hi:[1,0]
	v_pk_mul_f32 v[58:59], v[32:33], v[40:41] op_sel_hi:[1,0]
	s_mov_b64 s[2:3], 0
	s_waitcnt vmcnt(0)
	v_pk_mul_f32 v[42:43], v[56:57], v[42:43]
	v_pk_mul_f32 v[44:45], v[58:59], v[44:45]
	v_cvt_pk_bf16_f32 v42, v42, v43
	v_cvt_pk_bf16_f32 v43, v44, v45
	global_store_dwordx2 v[38:39], v[42:43], off
	global_load_dwordx4 v[42:45], v[36:37], off offset:1024 nt
	v_pk_mul_f32 v[56:57], v[26:27], v[40:41] op_sel_hi:[1,0]
	v_pk_mul_f32 v[58:59], v[28:29], v[40:41] op_sel_hi:[1,0]
	s_waitcnt vmcnt(0)
	v_pk_mul_f32 v[42:43], v[56:57], v[42:43]
	v_pk_mul_f32 v[44:45], v[58:59], v[44:45]
	v_cvt_pk_bf16_f32 v42, v42, v43
	v_cvt_pk_bf16_f32 v43, v44, v45
	global_store_dwordx2 v[38:39], v[42:43], off offset:512
	global_load_dwordx4 v[42:45], v[36:37], off offset:2048 nt
	v_pk_mul_f32 v[56:57], v[22:23], v[40:41] op_sel_hi:[1,0]
	v_pk_mul_f32 v[58:59], v[24:25], v[40:41] op_sel_hi:[1,0]
	s_waitcnt vmcnt(0)
	v_pk_mul_f32 v[42:43], v[56:57], v[42:43]
	v_pk_mul_f32 v[44:45], v[58:59], v[44:45]
	v_cvt_pk_bf16_f32 v42, v42, v43
	v_cvt_pk_bf16_f32 v43, v44, v45
	global_store_dwordx2 v[38:39], v[42:43], off offset:1024
	global_load_dwordx4 v[42:45], v[36:37], off offset:3072 nt
	v_pk_mul_f32 v[56:57], v[18:19], v[40:41] op_sel_hi:[1,0]
	v_pk_mul_f32 v[58:59], v[20:21], v[40:41] op_sel_hi:[1,0]
	s_waitcnt vmcnt(0)
	v_pk_mul_f32 v[42:43], v[56:57], v[42:43]
	v_pk_mul_f32 v[44:45], v[58:59], v[44:45]

; #define GAS __attribute__((address_space(1)))
; __device__ __forceinline__ unsigned pk2(float lo, float hi) { const pkf2_t v = {lo, hi}; const pkb2_t b = __builtin_convertvector(v, pkb2_t); return __builtin_bit_cast(unsigned, b); }
; __device__ __forceinline__ void p0_rows(Frame& F) {
;     ...
;         const float ra = __builtin_amdgcn_rsqf(wave_sum(sa) * (1.f / D) + EPS), rb = __builtin_amdgcn_rsqf(wave_sum(sb) * (1.f / D) + EPS);
;         GAS unsigned long long* oa = (GAS unsigned long long*)row_dst(m) + F.lane; GAS unsigned long long* ob = (GAS unsigned long long*)row_dst(two ? m2 : m) + F.lane;
;         float* rstd1 = (float*)F.KK;
;         if (m < MT) { if (F.lane == 0) rstd1[m] = ra;
; #pragma unroll
;             for (int j = 0; j < 4; ++j) oa[64 * j] = (unsigned long long)pk2(va[j].x, va[j].y) | ((unsigned long long)pk2(va[j].z, va[j].w) << 32); }
;         else { const GAS f32x4* ga = (const GAS f32x4*)F.mem_norm_g + F.lane;
; #pragma unroll
;             for (int j = 0; j < 4; ++j) { const f32x4 g1 = ga[64 * j]; oa[64 * j] = (unsigned long long)pk2(va[j].x * ra * g1.x, va[j].y * ra * g1.y) | ((unsigned long long)pk2(va[j].z * ra * g1.z, va[j].w * ra * g1.w) << 32); } }
;         if (two) {
;             if (m2 < MT) { if (F.lane == 0) rstd1[m2] = rb;
; #pragma unroll
;                 for (int j = 0; j < 4; ++j) ob[64 * j] = (unsigned long long)pk2(vb[j].x, vb[j].y) | ((unsigned long long)pk2(vb[j].z, vb[j].w) << 32); }
;             else { const GAS f32x4* gb = (const GAS f32x4*)F.mem_norm_g + F.lane;
; #pragma unroll
;                 for (int j = 0; j < 4; ++j) { const f32x4 g2 = gb[64 * j]; ob[64 * j] = (unsigned long long)pk2(vb[j].x * rb * g2.x, vb[j].y * rb * g2.y) | ((unsigned long long)pk2(vb[j].z * rb * g2.z, vb[j].w * rb * g2.w) << 32); } } }
.LBB0_42:
	v_cvt_pk_bf16_f32 v18, v42, v43
	v_cvt_pk_bf16_f32 v19, v44, v45
	s_andn2_b64 vcc, exec, s[20:21]
	global_store_dwordx2 v[38:39], v[18:19], off offset:1536
	s_cbranch_vccnz .LBB0_19
	s_add_i32 s2, s18, 0xffffbc00
	s_ashr_i32 s3, s18, 31
	s_waitcnt lgkmcnt(0)
	v_add_f32_e32 v18, v53, v54
	s_cmpk_lt_i32 s18, 0x4400
	v_fmamk_f32 v18, v18, 0x3a800000, v52
	s_cselect_b32 s3, s3, 0
	s_cselect_b32 s2, s18, s2
	v_rsq_f32_e32 v20, v18
	s_cselect_b32 s4, s65, s78
	s_cselect_b32 s5, s64, s89
	s_lshl_b64 s[2:3], s[2:3], 11
	s_add_u32 s2, s5, s2
	s_addc_u32 s3, s4, s3
	v_lshl_add_u64 v[18:19], s[2:3], 0, v[34:35]
	s_cmpk_lt_i32 s14, 0x4400
	s_mov_b64 s[2:3], -1
	s_cbranch_scc1 .LBB0_45
	global_load_dwordx4 v[22:25], v[36:37], off nt
	v_pk_mul_f32 v[26:27], v[14:15], v[20:21] op_sel_hi:[1,0]
	v_pk_mul_f32 v[28:29], v[16:17], v[20:21] op_sel_hi:[1,0]
	s_mov_b64 s[2:3], 0
	s_waitcnt vmcnt(0)
	v_pk_mul_f32 v[22:23], v[26:27], v[22:23]
	v_pk_mul_f32 v[24:25], v[28:29], v[24:25]
	v_cvt_pk_bf16_f32 v22, v22, v23
	v_cvt_pk_bf16_f32 v23, v24, v25
	global_store_dwordx2 v[18:19], v[22:23], off
	global_load_dwordx4 v[22:25], v[36:37], off offset:1024 nt
	v_pk_mul_f32 v[26:27], v[10:11], v[20:21] op_sel_hi:[1,0]
	v_pk_mul_f32 v[28:29], v[12:13], v[20:21] op_sel_hi:[1,0]
	s_waitcnt vmcnt(0)
	v_pk_mul_f32 v[22:23], v[26:27], v[22:23]
	v_pk_mul_f32 v[24:25], v[28:29], v[24:25]
	v_cvt_pk_bf16_f32 v22, v22, v23
	v_cvt_pk_bf16_f32 v23, v24, v25
	global_store_dwordx2 v[18:19], v[22:23], off offset:512
	global_load_dwordx4 v[22:25], v[36:37], off offset:2048 nt
	v_pk_mul_f32 v[26:27], v[6:7], v[20:21] op_sel_hi:[1,0]
	v_pk_mul_f32 v[28:29], v[8:9], v[20:21] op_sel_hi:[1,0]
	s_waitcnt vmcnt(0)
	v_pk_mul_f32 v[22:23], v[26:27], v[22:23]
	v_pk_mul_f32 v[24:25], v[28:29], v[24:25]
	v_cvt_pk_bf16_f32 v22, v22, v23
	v_cvt_pk_bf16_f32 v23, v24, v25
	global_store_dwordx2 v[18:19], v[22:23], off offset:1024
	global_load_dwordx4 v[22:25], v[36:37], off offset:3072 nt
	v_pk_mul_f32 v[26:27], v[2:3], v[20:21] op_sel_hi:[1,0]
	v_pk_mul_f32 v[28:29], v[4:5], v[20:21] op_sel_hi:[1,0]
	s_waitcnt vmcnt(0)
	v_pk_mul_f32 v[22:23], v[26:27], v[22:23]
	v_pk_mul_f32 v[24:25], v[28:29], v[24:25]

; #define GAS __attribute__((address_space(1)))
; __device__ __forceinline__ unsigned pk2(float lo, float hi) { const pkf2_t v = {lo, hi}; const pkb2_t b = __builtin_convertvector(v, pkb2_t); return __builtin_bit_cast(unsigned, b); }
; __device__ __forceinline__ void p0_rows(Frame& F) {
;     ...
;     for (int m = gw; m < MT + MEMR; m += 2 * NGW) {
;         const int m2 = m + NGW; const bool two = m2 < MT + MEMR;
;         const GAS f32x4* xa = (const GAS f32x4*)row_src(m) + F.lane; const GAS f32x4* xb = (const GAS f32x4*)row_src(two ? m2 : m) + F.lane;
;         f32x4 va[4], vb[4]; float sa = 0.f, sb = 0.f;
; #pragma unroll
;         for (int j = 0; j < 4; ++j) { va[j] = xa[64 * j]; vb[j] = xb[64 * j]; }
; #pragma unroll
;         for (int j = 0; j < 4; ++j) { sa += (va[j].x * va[j].x + va[j].y * va[j].y) + (va[j].z * va[j].z + va[j].w * va[j].w); sb += (vb[j].x * vb[j].x + vb[j].y * vb[j].y) + (vb[j].z * vb[j].z + vb[j].w * vb[j].w); }
;         const float ra = __builtin_amdgcn_rsqf(wave_sum(sa) * (1.f / D) + EPS), rb = __builtin_amdgcn_rsqf(wave_sum(sb) * (1.f / D) + EPS);
;         GAS unsigned long long* oa = (GAS unsigned long long*)row_dst(m) + F.lane; GAS unsigned long long* ob = (GAS unsigned long long*)row_dst(two ? m2 : m) + F.lane;
;         float* rstd1 = (float*)F.KK;
;         if (m < MT) { if (F.lane == 0) rstd1[m] = ra;
; #pragma unroll
;             for (int j = 0; j < 4; ++j) oa[64 * j] = (unsigned long long)pk2(va[j].x, va[j].y) | ((unsigned long long)pk2(va[j].z, va[j].w) << 32); }
;         else { const GAS f32x4* ga = (const GAS f32x4*)F.mem_norm_g + F.lane;
; #pragma unroll
;             for (int j = 0; j < 4; ++j) { const f32x4 g1 = ga[64 * j]; oa[64 * j] = (unsigned long long)pk2(va[j].x * ra * g1.x, va[j].y * ra * g1.y) | ((unsigned long long)pk2(va[j].z * ra * g1.z, va[j].w * ra * g1.w) << 32); } }
.LBB0_116:
	s_lshl_b64 s[10:11], s[22:23], 12
	s_add_u32 s4, s4, s10
	s_addc_u32 s5, s5, s11
	global_load_dwordx4 v[30:33], v51, s[4:5] nt
	global_load_dwordx4 v[26:29], v51, s[4:5] offset:1024 nt
	global_load_dwordx4 v[22:25], v51, s[4:5] offset:2048 nt
	global_load_dwordx4 v[18:21], v51, s[4:5] offset:3072 nt
	s_lshl_b64 s[4:5], s[8:9], 12
	s_add_u32 s2, s2, s4
	s_addc_u32 s3, s3, s5
	global_load_dwordx4 v[14:17], v51, s[2:3] nt
	global_load_dwordx4 v[10:13], v51, s[2:3] offset:1024 nt
	global_load_dwordx4 v[6:9], v51, s[2:3] offset:2048 nt
	global_load_dwordx4 v[2:5], v51, s[2:3] offset:3072 nt
	s_add_i32 s4, s6, 0xffffbc00
	s_ashr_i32 s7, s6, 31
	s_cmpk_lt_i32 s6, 0x4400
	s_cselect_b64 s[2:3], -1, 0
	s_and_b64 vcc, s[2:3], exec
	s_cselect_b32 s3, s7, 0
	s_cselect_b32 s2, s6, s4
	s_cselect_b32 s4, s65, s78
	s_cselect_b32 s5, s64, s89
	s_lshl_b64 s[2:3], s[2:3], 11
	s_add_u32 s2, s5, s2
	s_addc_u32 s3, s4, s3
	s_waitcnt vmcnt(7)
	v_mul_f32_e32 v38, v31, v31
	v_mul_f32_e32 v39, v33, v33
	s_waitcnt vmcnt(6)
	v_mul_f32_e32 v40, v27, v27
	v_mul_f32_e32 v42, v29, v29
	s_waitcnt vmcnt(5)
	v_mul_f32_e32 v43, v23, v23
	v_mul_f32_e32 v44, v25, v25
	v_fmac_f32_e32 v38, v30, v30
	v_fmac_f32_e32 v39, v32, v32
	v_fmac_f32_e32 v40, v26, v26
	v_fmac_f32_e32 v42, v28, v28
	s_waitcnt vmcnt(4)
	v_mul_f32_e32 v45, v19, v19
	v_mul_f32_e32 v53, v21, v21
	v_fmac_f32_e32 v43, v22, v22
	v_fmac_f32_e32 v44, v24, v24
	v_add_f32_e32 v38, v38, v39
	v_add_f32_e32 v40, v40, v42
	v_fmac_f32_e32 v45, v18, v18
	v_fmac_f32_e32 v53, v20, v20
	v_add_f32_e32 v43, v43, v44
	v_add_f32_e32 v38, v38, v40
	s_waitcnt vmcnt(2)
	v_mul_f32_e32 v42, v11, v11
	v_mul_f32_e32 v55, v13, v13
	s_waitcnt vmcnt(1)
	v_mul_f32_e32 v44, v7, v7
	v_mul_f32_e32 v56, v9, v9
	v_add_f32_e32 v45, v45, v53
	v_add_f32_e32 v38, v38, v43
	v_fmac_f32_e32 v42, v10, v10
	v_fmac_f32_e32 v55, v12, v12
	v_fmac_f32_e32 v44, v6, v6
	v_fmac_f32_e32 v56, v8, v8
	v_add_f32_e32 v38, v38, v45
	v_mul_f32_e32 v39, v15, v15
	s_waitcnt lgkmcnt(0)
	v_mul_f32_e32 v54, v17, v17
	v_add_f32_e32 v40, v42, v55
	v_add_f32_e32 v42, v44, v56
	ds_bpermute_b32 v44, v41, v38
	v_fmac_f32_e32 v39, v14, v14
	v_fmac_f32_e32 v54, v16, v16
	s_waitcnt vmcnt(0)
	v_mul_f32_e32 v53, v3, v3
	v_mul_f32_e32 v57, v5, v5
	v_add_f32_e32 v39, v39, v54
	v_fmac_f32_e32 v53, v2, v2
	v_fmac_f32_e32 v57, v4, v4
	v_add_f32_e32 v39, v39, v40
	v_add_f32_e32 v43, v53, v57
	v_add_f32_e32 v39, v39, v42
	v_add_f32_e32 v39, v39, v43
	s_waitcnt lgkmcnt(0)
	v_add_f32_e32 v38, v38, v44
	ds_bpermute_b32 v40, v41, v39
	ds_bpermute_b32 v42, v46, v38
	s_waitcnt lgkmcnt(1)
	v_add_f32_e32 v39, v39, v40
	s_waitcnt lgkmcnt(0)
	v_add_f32_e32 v38, v38, v42
	ds_bpermute_b32 v40, v46, v39
	ds_bpermute_b32 v42, v47, v38
	s_waitcnt lgkmcnt(1)
	v_add_f32_e32 v39, v39, v40
	s_waitcnt lgkmcnt(0)
	v_add_f32_e32 v38, v38, v42
	ds_bpermute_b32 v40, v47, v39
	ds_bpermute_b32 v42, v48, v38
	s_waitcnt lgkmcnt(1)
	v_add_f32_e32 v39, v39, v40
	s_waitcnt lgkmcnt(0)
	v_add_f32_e32 v38, v38, v42
	ds_bpermute_b32 v40, v48, v39
	ds_bpermute_b32 v42, v49, v38
	s_waitcnt lgkmcnt(1)
	v_add_f32_e32 v39, v39, v40
	s_waitcnt lgkmcnt(0)
	v_add_f32_e32 v38, v38, v42
	ds_bpermute_b32 v40, v49, v39
	ds_bpermute_b32 v42, v50, v38
	s_waitcnt lgkmcnt(1)
	v_add_f32_e32 v53, v39, v40
	s_waitcnt lgkmcnt(0)
	v_add_f32_e32 v38, v38, v42
	ds_bpermute_b32 v54, v50, v53
	v_fmamk_f32 v38, v38, 0x3a800000, v52
	v_rsq_f32_e32 v40, v38
	v_lshl_add_u64 v[38:39], s[2:3], 0, v[34:35]
	s_mov_b64 s[2:3], -1
	s_cbranch_vccnz .LBB0_118
	global_load_dwordx4 v[42:45], v[36:37], off nt
	v_pk_mul_f32 v[56:57], v[30:31], v[40:41] op_sel_hi:[1,0]
	v_pk_mul_f32 v[58:59], v[32:33], v[40:41] op_sel_hi:[1,0]
	s_mov_b64 s[2:3], 0
	s_waitcnt vmcnt(0)
	v_pk_mul_f32 v[42:43], v[56:57], v[42:43]
	v_pk_mul_f32 v[44:45], v[58:59], v[44:45]
	v_cvt_pk_bf16_f32 v42, v42, v43
	v_cvt_pk_bf16_f32 v43, v44, v45
	global_store_dwordx2 v[38:39], v[42:43], off
	global_load_dwordx4 v[42:45], v[36:37], off offset:1024 nt
	v_pk_mul_f32 v[56:57], v[26:27], v[40:41] op_sel_hi:[1,0]
	v_pk_mul_f32 v[58:59], v[28:29], v[40:41] op_sel_hi:[1,0]
	s_waitcnt vmcnt(0)
	v_pk_mul_f32 v[42:43], v[56:57], v[42:43]
	v_pk_mul_f32 v[44:45], v[58:59], v[44:45]
	v_cvt_pk_bf16_f32 v42, v42, v43
	v_cvt_pk_bf16_f32 v43, v44, v45
	global_store_dwordx2 v[38:39], v[42:43], off offset:512
	global_load_dwordx4 v[42:45], v[36:37], off offset:2048 nt
	v_pk_mul_f32 v[56:57], v[22:23], v[40:41] op_sel_hi:[1,0]
	v_pk_mul_f32 v[58:59], v[24:25], v[40:41] op_sel_hi:[1,0]
	s_waitcnt vmcnt(0)
	v_pk_mul_f32 v[42:43], v[56:57], v[42:43]
	v_pk_mul_f32 v[44:45], v[58:59], v[44:45]
	v_cvt_pk_bf16_f32 v42, v42, v43
	v_cvt_pk_bf16_f32 v43, v44, v45
	global_store_dwordx2 v[38:39], v[42:43], off offset:1024
	global_load_dwordx4 v[42:45], v[36:37], off offset:3072 nt
	v_pk_mul_f32 v[56:57], v[18:19], v[40:41] op_sel_hi:[1,0]
	v_pk_mul_f32 v[58:59], v[20:21], v[40:41] op_sel_hi:[1,0]
	s_waitcnt vmcnt(0)
	v_pk_mul_f32 v[42:43], v[56:57], v[42:43]
	v_pk_mul_f32 v[44:45], v[58:59], v[44:45]

; #define GAS __attribute__((address_space(1)))
; __device__ __forceinline__ unsigned pk2(float lo, float hi) { const pkf2_t v = {lo, hi}; const pkb2_t b = __builtin_convertvector(v, pkb2_t); return __builtin_bit_cast(unsigned, b); }
; __device__ __forceinline__ void p0_rows(Frame& F) {
;     ...
;         const float ra = __builtin_amdgcn_rsqf(wave_sum(sa) * (1.f / D) + EPS), rb = __builtin_amdgcn_rsqf(wave_sum(sb) * (1.f / D) + EPS);
;         GAS unsigned long long* oa = (GAS unsigned long long*)row_dst(m) + F.lane; GAS unsigned long long* ob = (GAS unsigned long long*)row_dst(two ? m2 : m) + F.lane;
;         float* rstd1 = (float*)F.KK;
;         if (m < MT) { if (F.lane == 0) rstd1[m] = ra;
; #pragma unroll
;             for (int j = 0; j < 4; ++j) oa[64 * j] = (unsigned long long)pk2(va[j].x, va[j].y) | ((unsigned long long)pk2(va[j].z, va[j].w) << 32); }
;         else { const GAS f32x4* ga = (const GAS f32x4*)F.mem_norm_g + F.lane;
; #pragma unroll
;             for (int j = 0; j < 4; ++j) { const f32x4 g1 = ga[64 * j]; oa[64 * j] = (unsigned long long)pk2(va[j].x * ra * g1.x, va[j].y * ra * g1.y) | ((unsigned long long)pk2(va[j].z * ra * g1.z, va[j].w * ra * g1.w) << 32); } }
;         if (two) {
;             if (m2 < MT) { if (F.lane == 0) rstd1[m2] = rb;
; #pragma unroll
;                 for (int j = 0; j < 4; ++j) ob[64 * j] = (unsigned long long)pk2(vb[j].x, vb[j].y) | ((unsigned long long)pk2(vb[j].z, vb[j].w) << 32); }
;             else { const GAS f32x4* gb = (const GAS f32x4*)F.mem_norm_g + F.lane;
; #pragma unroll
;                 for (int j = 0; j < 4; ++j) { const f32x4 g2 = gb[64 * j]; ob[64 * j] = (unsigned long long)pk2(vb[j].x * rb * g2.x, vb[j].y * rb * g2.y) | ((unsigned long long)pk2(vb[j].z * rb * g2.z, vb[j].w * rb * g2.w) << 32); } } }
.LBB0_122:
	v_cvt_pk_bf16_f32 v18, v42, v43
	v_cvt_pk_bf16_f32 v19, v44, v45
	s_andn2_b64 vcc, exec, s[20:21]
	global_store_dwordx2 v[38:39], v[18:19], off offset:1536
	s_cbranch_vccnz .LBB0_99
	s_add_i32 s2, s18, 0xffffbc00
	s_ashr_i32 s3, s18, 31
	s_waitcnt lgkmcnt(0)
	v_add_f32_e32 v18, v53, v54
	s_cmpk_lt_i32 s18, 0x4400
	v_fmamk_f32 v18, v18, 0x3a800000, v52
	s_cselect_b32 s3, s3, 0
	s_cselect_b32 s2, s18, s2
	v_rsq_f32_e32 v20, v18
	s_cselect_b32 s4, s65, s78
	s_cselect_b32 s5, s64, s89
	s_lshl_b64 s[2:3], s[2:3], 11
	s_add_u32 s2, s5, s2
	s_addc_u32 s3, s4, s3
	v_lshl_add_u64 v[18:19], s[2:3], 0, v[34:35]
	s_cmpk_lt_i32 s16, 0x4400
	s_mov_b64 s[2:3], -1
	s_cbranch_scc1 .LBB0_125
	global_load_dwordx4 v[22:25], v[36:37], off nt
	v_pk_mul_f32 v[26:27], v[14:15], v[20:21] op_sel_hi:[1,0]
	v_pk_mul_f32 v[28:29], v[16:17], v[20:21] op_sel_hi:[1,0]
	s_mov_b64 s[2:3], 0
	s_waitcnt vmcnt(0)
	v_pk_mul_f32 v[22:23], v[26:27], v[22:23]
	v_pk_mul_f32 v[24:25], v[28:29], v[24:25]
	v_cvt_pk_bf16_f32 v22, v22, v23
	v_cvt_pk_bf16_f32 v23, v24, v25
	global_store_dwordx2 v[18:19], v[22:23], off
	global_load_dwordx4 v[22:25], v[36:37], off offset:1024 nt
	v_pk_mul_f32 v[26:27], v[10:11], v[20:21] op_sel_hi:[1,0]
	v_pk_mul_f32 v[28:29], v[12:13], v[20:21] op_sel_hi:[1,0]
	s_waitcnt vmcnt(0)
	v_pk_mul_f32 v[22:23], v[26:27], v[22:23]
	v_pk_mul_f32 v[24:25], v[28:29], v[24:25]
	v_cvt_pk_bf16_f32 v22, v22, v23
	v_cvt_pk_bf16_f32 v23, v24, v25
	global_store_dwordx2 v[18:19], v[22:23], off offset:512
	global_load_dwordx4 v[22:25], v[36:37], off offset:2048 nt
	v_pk_mul_f32 v[26:27], v[6:7], v[20:21] op_sel_hi:[1,0]
	v_pk_mul_f32 v[28:29], v[8:9], v[20:21] op_sel_hi:[1,0]
	s_waitcnt vmcnt(0)
	v_pk_mul_f32 v[22:23], v[26:27], v[22:23]
	v_pk_mul_f32 v[24:25], v[28:29], v[24:25]
	v_cvt_pk_bf16_f32 v22, v22, v23
	v_cvt_pk_bf16_f32 v23, v24, v25
	global_store_dwordx2 v[18:19], v[22:23], off offset:1024
	global_load_dwordx4 v[22:25], v[36:37], off offset:3072 nt
	v_pk_mul_f32 v[26:27], v[2:3], v[20:21] op_sel_hi:[1,0]
	v_pk_mul_f32 v[28:29], v[4:5], v[20:21] op_sel_hi:[1,0]
	s_waitcnt vmcnt(0)
	v_pk_mul_f32 v[22:23], v[26:27], v[22:23]
	v_pk_mul_f32 v[24:25], v[28:29], v[24:25]
